# attention: one static priority raise for waves 4-7 during the key loop (reset after it)
# baseline (speedup 1.0000x reference)
.Lattn_skip_b1:
	s_cmp_eq_u32 s11, 1
	s_cbranch_scc0 .Lattn_prio_n
	s_setprio 1

.Lattn_skip_b2:
	s_setprio 0
	v_and_b32_e32 v2, 64, v220
	v_xor_b32_e32 v0, 32, v220
	v_add_u32_e32 v2, 64, v2
	v_cmp_lt_i32_e32 vcc, v0, v2
	s_lshl_b32 s2, s8, 14
	s_add_i32 s2, s2, 0
	v_cndmask_b32_e32 v0, v220, v0, vcc
	s_waitcnt vmcnt(1)
	v_lshlrev_b32_e32 v121, 2, v0
	ds_bpermute_b32 v0, v121, v182
	s_cmp_eq_u32 s11, 1
	v_lshl_add_u32 v2, v170, 2, s2
	s_waitcnt lgkmcnt(0)
	v_add_f32_e32 v0, v182, v0
	s_cbranch_scc0 .LBB0_128
	v_div_scale_f32 v3, s[2:3], v0, v0, v166
	v_rcp_f32_e32 v4, v3
	v_div_scale_f32 v5, vcc, v166, v0, v166
	v_fma_f32 v6, -v3, v4, 1.0
	v_fmac_f32_e32 v4, v6, v4
	v_mul_f32_e32 v6, v5, v4
	v_fma_f32 v7, -v3, v6, v5
	v_fmac_f32_e32 v6, v7, v4
	v_fma_f32 v3, -v3, v6, v5
	v_div_fmas_f32 v3, v3, v4, v6
	v_div_fixup_f32 v3, v3, v0, v166
	v_mul_f32_e32 v4, v64, v3
	v_mul_f32_e32 v5, v65, v3
	ds_write2st64_b32 v2, v4, v5 offset1:1
	v_mul_f32_e32 v4, v66, v3
	v_mul_f32_e32 v5, v67, v3
	ds_write2st64_b32 v2, v4, v5 offset0:2 offset1:3
	v_mul_f32_e32 v4, v68, v3
	v_mul_f32_e32 v5, v69, v3
	ds_write2st64_b32 v2, v4, v5 offset0:4 offset1:5
	v_mul_f32_e32 v4, v70, v3
	v_mul_f32_e32 v5, v71, v3
	ds_write2st64_b32 v2, v4, v5 offset0:6 offset1:7
	v_mul_f32_e32 v4, v72, v3
	v_mul_f32_e32 v5, v73, v3
	ds_write2st64_b32 v2, v4, v5 offset0:8 offset1:9
	v_mul_f32_e32 v4, v74, v3
	v_mul_f32_e32 v5, v75, v3
	ds_write2st64_b32 v2, v4, v5 offset0:10 offset1:11
	v_mul_f32_e32 v4, v76, v3
	v_mul_f32_e32 v5, v77, v3
	ds_write2st64_b32 v2, v4, v5 offset0:12 offset1:13
	v_mul_f32_e32 v4, v78, v3
	v_mul_f32_e32 v5, v79, v3
	ds_write2st64_b32 v2, v4, v5 offset0:14 offset1:15
	v_mul_f32_e32 v4, v48, v3
	v_mul_f32_e32 v5, v49, v3
	ds_write2st64_b32 v2, v4, v5 offset0:16 offset1:17
	v_mul_f32_e32 v4, v50, v3
	v_mul_f32_e32 v5, v51, v3
	ds_write2st64_b32 v2, v4, v5 offset0:18 offset1:19
	v_mul_f32_e32 v4, v52, v3
	v_mul_f32_e32 v5, v53, v3
	ds_write2st64_b32 v2, v4, v5 offset0:20 offset1:21
	v_mul_f32_e32 v4, v54, v3
	v_mul_f32_e32 v5, v55, v3
	ds_write2st64_b32 v2, v4, v5 offset0:22 offset1:23
	v_mul_f32_e32 v4, v56, v3
	v_mul_f32_e32 v5, v57, v3
	ds_write2st64_b32 v2, v4, v5 offset0:24 offset1:25
	v_mul_f32_e32 v4, v58, v3
	v_mul_f32_e32 v5, v59, v3
	ds_write2st64_b32 v2, v4, v5 offset0:26 offset1:27
	v_mul_f32_e32 v4, v60, v3
	v_mul_f32_e32 v5, v61, v3
	ds_write2st64_b32 v2, v4, v5 offset0:28 offset1:29
	v_mul_f32_e32 v4, v62, v3
	v_mul_f32_e32 v5, v63, v3
	ds_write2st64_b32 v2, v4, v5 offset0:30 offset1:31
	v_mul_f32_e32 v4, v32, v3
	v_mul_f32_e32 v5, v33, v3
	ds_write2st64_b32 v2, v4, v5 offset0:32 offset1:33
	v_mul_f32_e32 v4, v34, v3
	v_mul_f32_e32 v5, v35, v3
	ds_write2st64_b32 v2, v4, v5 offset0:34 offset1:35
	v_mul_f32_e32 v4, v36, v3
	v_mul_f32_e32 v5, v37, v3
	ds_write2st64_b32 v2, v4, v5 offset0:36 offset1:37
	v_mul_f32_e32 v4, v38, v3
	v_mul_f32_e32 v5, v39, v3
	ds_write2st64_b32 v2, v4, v5 offset0:38 offset1:39
	v_mul_f32_e32 v4, v40, v3
	v_mul_f32_e32 v5, v41, v3
	ds_write2st64_b32 v2, v4, v5 offset0:40 offset1:41
	v_mul_f32_e32 v4, v42, v3
	v_mul_f32_e32 v5, v43, v3
	ds_write2st64_b32 v2, v4, v5 offset0:42 offset1:43
	v_mul_f32_e32 v4, v44, v3
	v_mul_f32_e32 v5, v45, v3
	ds_write2st64_b32 v2, v4, v5 offset0:44 offset1:45
	v_mul_f32_e32 v4, v46, v3
	v_mul_f32_e32 v5, v47, v3
	ds_write2st64_b32 v2, v4, v5 offset0:46 offset1:47
	v_mul_f32_e32 v4, v16, v3
	v_mul_f32_e32 v5, v17, v3
	ds_write2st64_b32 v2, v4, v5 offset0:48 offset1:49
	v_mul_f32_e32 v4, v18, v3
	v_mul_f32_e32 v5, v19, v3
	ds_write2st64_b32 v2, v4, v5 offset0:50 offset1:51
	v_mul_f32_e32 v4, v20, v3
	v_mul_f32_e32 v5, v21, v3
	ds_write2st64_b32 v2, v4, v5 offset0:52 offset1:53
	v_mul_f32_e32 v4, v22, v3
	v_mul_f32_e32 v5, v23, v3
	ds_write2st64_b32 v2, v4, v5 offset0:54 offset1:55
	v_mul_f32_e32 v4, v24, v3
	v_mul_f32_e32 v5, v25, v3
	ds_write2st64_b32 v2, v4, v5 offset0:56 offset1:57
	v_mul_f32_e32 v4, v26, v3
	v_mul_f32_e32 v5, v27, v3
	ds_write2st64_b32 v2, v4, v5 offset0:58 offset1:59
	v_mul_f32_e32 v4, v28, v3
	v_mul_f32_e32 v5, v29, v3
	ds_write2st64_b32 v2, v4, v5 offset0:60 offset1:61
	v_mul_f32_e32 v4, v30, v3
	v_mul_f32_e32 v3, v31, v3
	ds_write2st64_b32 v2, v4, v3 offset0:62 offset1:63
